# chain compute waves get a private loop tail (no dead VALU, fewer taken branches); KV-cache copy loop moved to the 192 workgroups with only 4 prep items; rest as previous
# speedup vs baseline: 1.0321x; 1.0002x over previous
; __global__ void __launch_bounds__(NTHR, 2) hybrid_fwd(Args args) {
;     ...
;         const int gt = bx * NTHR + tid, NGT = G * NTHR;
;         for (int idx = gt; idx < 2 * (131072 + 1048576); idx += NGT) {
;             if (idx < 262144) { const int which = idx >> 17, r = idx & 131071, b = r >> 15, j = (r >> 8) & 127, c = r & 255;
;                 out[O_KP + idx] = __uint_as_float((unsigned)Zb[(size_t)(b * 8192 + 8064 + j) * DIN + ZK + which * 256 + c] << 16); }
;             else { const int r2 = idx - 262144, which = r2 >> 20, r = r2 & 1048575, s = r >> 15, j = (r >> 8) & 127, c = r & 255;
;                 float v;
;                 if (j < 64) v = args.in[which ? I_CV : I_CK][(size_t)(s * 128 + 64 + j) * 256 + c];
;                 else v = __uint_as_float((unsigned)Zb[(size_t)(MP + s * 64 + j - 64) * DIN + ZK + which * 256 + c] << 16);
;                 out[O_KS + r2] = v; }
;         }
.LBB0_435:
	v_readlane_b32 s0, v236, 6
	v_readlane_b32 s1, v236, 7
	s_waitcnt vmcnt(0)
	s_sub_i32 s0, s0, 64
	s_cmp_lt_i32 s0, 0
	s_cselect_b32 s0, 0x2000, s0
	v_lshl_add_u32 v0, s0, 9, v129
	s_mov_b32 s0, 0x240000
	v_cmp_gt_i32_e32 vcc, s0, v0
	s_and_saveexec_b64 s[0:1], vcc
	v_readlane_b32 s42, v236, 4
	v_readlane_b32 s43, v236, 5
	s_cbranch_execz .LBB0_446
	s_mov_b32 s2, 0x18000
	v_ashrrev_i32_e32 v5, 31, v0
	v_mov_b32_e32 v4, v0
	v_and_b32_e32 v2, 0xff, v129
	v_lshl_add_u64 v[4:5], v[4:5], 2, s[84:85]
	s_mov_b64 s[4:5], 0x11000000
	s_ashr_i32 s3, s2, 31
	v_mov_b32_e32 v1, 0
	v_lshl_add_u64 v[4:5], v[4:5], 0, s[4:5]
	s_lshl_b64 s[4:5], s[2:3], 2
	s_mov_b64 s[6:7], 0
	s_mov_b32 s3, 0x3ffff
	s_mov_b32 s14, 0x100000
	s_movk_i32 s15, 0x6000
	s_mov_b32 s16, 0x23ffff
	v_lshlrev_b32_e32 v6, 1, v2
	s_branch .LBB0_438

; #define LAS __attribute__((address_space(3)))
; #define CH_RAWBAR() do { asm volatile("s_waitcnt lgkmcnt(0)" ::: "memory"); __builtin_amdgcn_s_barrier(); asm volatile("" ::: "memory"); } while (0)
; #define CH_WAIT(EX) do { if (wave < 3) CH_WAITN(8 + (EX)); else if (wave == 3) CH_WAITN(6 + (EX)); else CH_WAITN(6); } while (0)
; __device__ __forceinline__ void hgrn_chain(const unsigned char* REC, const float* s0, float* sout, bf16_t* MIX,
;                                            int cidx0, int nchunks, int h, int vhalf, LAS unsigned char* lds, int wave, int lane) {
;     ...
;         ch_issue(Ri, lds + islot * CH_SLOT, wave); Ri = Ri < Rlast ? Ri + 8 * REC_STRIDE : Rlast;
;         islot = islot == CH_NS - 1 ? 0 : islot + 1;
;         const LAS unsigned char* R = lds + slot * CH_SLOT;
;         slot = slot == CH_NS - 1 ? 0 : slot + 1;
;     ...
;         if (c == 0) CH_WAIT(2); else if (c == 1) CH_WAIT(4); else CH_WAIT(6);
;         CH_RAWBAR();
.LBB0_604:
	s_add_i32 s12, s15, 1
	s_cmp_lg_u32 s15, 3
	s_cselect_b32 s15, s12, 0
	s_add_i32 s12, s16, 1
	s_cmp_lg_u32 s16, 3
	s_waitcnt lgkmcnt(0)
	s_barrier
	s_cselect_b32 s16, s12, 0
	s_add_i32 s11, s11, 1
	s_mov_b64 s[12:13], 0x20000
	s_cmpk_eq_i32 s11, 0x100
	v_lshl_add_u64 v[48:49], v[48:49], 0, s[12:13]
	s_cbranch_scc1 .LBB0_639

; __device__ __forceinline__ void hgrn_chain(const unsigned char* REC, const float* s0, float* sout, bf16_t* MIX,
;                                            int cidx0, int nchunks, int h, int vhalf, LAS unsigned char* lds, int wave, int lane) {
;     ...
;     for (int c = 0; c < nchunks; ++c) {
;         ch_issue(Ri, lds + islot * CH_SLOT, wave); Ri = Ri < Rlast ? Ri + 8 * REC_STRIDE : Rlast;
;         islot = islot == CH_NS - 1 ? 0 : islot + 1;
;         const LAS unsigned char* R = lds + slot * CH_SLOT;
;         slot = slot == CH_NS - 1 ? 0 : slot + 1;
;         if (comp) {
;             bf16x8 QDf[2][4], KEf[8], ITf, Af[2]; f32x4 DEC[8];
; #pragma unroll
;             for (int kb = 0; kb < 8; ++kb) { DEC[kb] = *(const LAS f32x4*)(R + R_DEC + (16 * kb + 4 * g) * 4); KEf[kb] = *(const LAS bf16x8*)(R + R_KE + ((16 * kb + c16) * 32 + 8 * g) * 2); }
;             ITf = *(const LAS bf16x8*)(R + R_IT + ((v0 + c16) * 32 + 8 * g) * 2);
; #pragma unroll
;             for (int tb = 0; tb < 2; ++tb) {
;                 Af[tb] = *(const LAS bf16x8*)(R + R_A + ((16 * tb + c16) * 32 + 8 * g) * 2);
; #pragma unroll
;                 for (int kk = 0; kk < 4; ++kk) QDf[tb][kk] = *(const LAS bf16x8*)(R + R_QD + ((tb * 4 + kk) * 64 + lane) * 16);
;             }
;             bf16x8 Sb[4];
; #pragma unroll
;             for (int kk = 0; kk < 4; ++kk) {
;                 u32x4 sb; sb.x = cvt_pk_bf16(S[2 * kk][0], S[2 * kk][1]); sb.y = cvt_pk_bf16(S[2 * kk][2], S[2 * kk][3]);
;                 sb.z = cvt_pk_bf16(S[2 * kk + 1][0], S[2 * kk + 1][1]); sb.w = cvt_pk_bf16(S[2 * kk + 1][2], S[2 * kk + 1][3]);
;                 Sb[kk] = __builtin_bit_cast(bf16x8, sb);
;             }
; #pragma unroll
;             for (int kb = 0; kb < 8; ++kb) S[kb] = __builtin_amdgcn_mfma_f32_16x16x32_bf16(KEf[kb], ITf, S[kb] * DEC[kb], 0, 0, 0);
;             f32x4 o0 = {0.f, 0.f, 0.f, 0.f}, o1 = o0;
;             o0 = __builtin_amdgcn_mfma_f32_16x16x32_bf16(ITf, Af[0], o0, 0, 0, 0);
;             o1 = __builtin_amdgcn_mfma_f32_16x16x32_bf16(ITf, Af[1], o1, 0, 0, 0);
; #pragma unroll
;             for (int kk = 0; kk < 4; ++kk) { o0 = __builtin_amdgcn_mfma_f32_16x16x32_bf16(Sb[kk], QDf[0][kk], o0, 0, 0, 0); o1 = __builtin_amdgcn_mfma_f32_16x16x32_bf16(Sb[kk], QDf[1][kk], o1, 0, 0, 0); }
;             u32x2 w; w.x = cvt_pk_bf16(o0[0], o0[1]); w.y = cvt_pk_bf16(o0[2], o0[3]);
.Lch_comp_loop:
	s_mul_i32 s12, s16, 0x6c00
	v_add_u32_e32 v36, s12, v61
	v_add_u32_e32 v39, s12, v120
	v_add_u32_e32 v37, v36, v63
	v_add_u32_e32 v38, v36, v62
	ds_read_b128 v[32:35], v38 offset:16384
	ds_read_b128 v[164:167], v36 offset:26624
	ds_read_b128 v[196:199], v37 offset:8192
	ds_read_b128 v[168:171], v36 offset:26688
	ds_read_b128 v[200:203], v37 offset:9216
	ds_read_b128 v[172:175], v36 offset:26752
	ds_read_b128 v[204:207], v37 offset:10240
	ds_read_b128 v[176:179], v36 offset:26816
	ds_read_b128 v[208:211], v37 offset:11264
	ds_read_b128 v[180:183], v36 offset:26880
	ds_read_b128 v[212:215], v37 offset:12288
	ds_read_b128 v[184:187], v36 offset:26944
	ds_read_b128 v[216:219], v37 offset:13312
	ds_read_b128 v[188:191], v36 offset:27008
	ds_read_b128 v[220:223], v37 offset:14336
	s_mov_b64 s[8:9], 0
	v_cvt_pk_bf16_f32 v110, v28, v29
	v_cvt_pk_bf16_f32 v111, v30, v31
	v_cvt_pk_bf16_f32 v112, v24, v25
	v_cvt_pk_bf16_f32 v113, v26, v27
	v_cvt_pk_bf16_f32 v114, v20, v21
	v_cvt_pk_bf16_f32 v115, v22, v23
	v_cvt_pk_bf16_f32 v116, v16, v17
	v_cvt_pk_bf16_f32 v117, v18, v19
	v_cvt_pk_bf16_f32 v130, v12, v13
	v_cvt_pk_bf16_f32 v131, v14, v15
	v_cvt_pk_bf16_f32 v132, v8, v9
	v_cvt_pk_bf16_f32 v133, v10, v11
	v_cvt_pk_bf16_f32 v134, v4, v5
	v_cvt_pk_bf16_f32 v135, v6, v7
	v_cvt_pk_bf16_f32 v136, v0, v1
	v_cvt_pk_bf16_f32 v137, v2, v3
	s_waitcnt lgkmcnt(12)
	v_pk_mul_f32 v[28:29], v[28:29], v[164:165]
	v_pk_mul_f32 v[30:31], v[30:31], v[166:167]
	ds_read_b128 v[192:195], v36 offset:27072
	ds_read_b128 v[224:227], v37 offset:15360
	v_mfma_f32_16x16x32_bf16 v[28:31], v[196:199], v[32:35], v[28:31]
	s_waitcnt lgkmcnt(12)
	v_pk_mul_f32 v[24:25], v[24:25], v[168:169]
	v_pk_mul_f32 v[26:27], v[26:27], v[170:171]
	ds_read_b128 v[228:231], v37 offset:24576
	ds_read_b128 v[232:235], v37 offset:25600
	v_mfma_f32_16x16x32_bf16 v[24:27], v[200:203], v[32:35], v[24:27]
	s_waitcnt lgkmcnt(12)
	v_pk_mul_f32 v[20:21], v[20:21], v[172:173]
	v_pk_mul_f32 v[22:23], v[22:23], v[174:175]
	ds_read_b128 v[78:81], v39
	ds_read_b128 v[82:85], v39 offset:4096
	v_mfma_f32_16x16x32_bf16 v[20:23], v[204:207], v[32:35], v[20:23]
	s_waitcnt lgkmcnt(12)
	v_pk_mul_f32 v[16:17], v[16:17], v[176:177]
	v_pk_mul_f32 v[18:19], v[18:19], v[178:179]
	ds_read_b128 v[86:89], v39 offset:1024
	ds_read_b128 v[90:93], v39 offset:5120
	v_mfma_f32_16x16x32_bf16 v[16:19], v[208:211], v[32:35], v[16:19]
	s_waitcnt lgkmcnt(12)
	v_pk_mul_f32 v[12:13], v[12:13], v[180:181]
	v_pk_mul_f32 v[14:15], v[14:15], v[182:183]
	ds_read_b128 v[94:97], v39 offset:2048
	ds_read_b128 v[98:101], v39 offset:6144
	v_mfma_f32_16x16x32_bf16 v[12:15], v[212:215], v[32:35], v[12:15]
	s_waitcnt lgkmcnt(12)
	v_pk_mul_f32 v[8:9], v[8:9], v[184:185]
	v_pk_mul_f32 v[10:11], v[10:11], v[186:187]
	ds_read_b128 v[102:105], v39 offset:3072
	ds_read_b128 v[106:109], v39 offset:7168
	v_mfma_f32_16x16x32_bf16 v[8:11], v[216:219], v[32:35], v[8:11]
	s_waitcnt lgkmcnt(12)
	v_pk_mul_f32 v[4:5], v[4:5], v[188:189]
	v_pk_mul_f32 v[6:7], v[6:7], v[190:191]
	s_nop 1
	v_mfma_f32_16x16x32_bf16 v[4:7], v[220:223], v[32:35], v[4:7]
	s_waitcnt lgkmcnt(10)
	v_pk_mul_f32 v[0:1], v[0:1], v[192:193]
	v_pk_mul_f32 v[2:3], v[2:3], v[194:195]
	s_nop 1
	v_mfma_f32_16x16x32_bf16 v[0:3], v[224:227], v[32:35], v[0:3]
	s_waitcnt lgkmcnt(8)
	v_mfma_f32_16x16x32_bf16 v[138:141], v[32:35], v[228:231], 0
	v_mfma_f32_16x16x32_bf16 v[146:149], v[32:35], v[232:235], 0
	s_waitcnt lgkmcnt(7)
	v_mfma_f32_16x16x32_bf16 v[138:141], v[110:113], v[78:81], v[138:141]
	s_waitcnt lgkmcnt(6)
	v_mfma_f32_16x16x32_bf16 v[146:149], v[110:113], v[82:85], v[146:149]
	s_waitcnt lgkmcnt(5)
	v_mfma_f32_16x16x32_bf16 v[138:141], v[114:117], v[86:89], v[138:141]
	s_waitcnt lgkmcnt(4)
	v_mfma_f32_16x16x32_bf16 v[146:149], v[114:117], v[90:93], v[146:149]
	s_waitcnt lgkmcnt(3)
	v_mfma_f32_16x16x32_bf16 v[138:141], v[130:133], v[94:97], v[138:141]
	s_waitcnt lgkmcnt(2)
	v_mfma_f32_16x16x32_bf16 v[146:149], v[130:133], v[98:101], v[146:149]
	s_waitcnt lgkmcnt(1)
	v_mfma_f32_16x16x32_bf16 v[138:141], v[134:137], v[102:105], v[138:141]
	s_waitcnt lgkmcnt(0)
	v_mfma_f32_16x16x32_bf16 v[146:149], v[134:137], v[106:109], v[146:149]
	s_mov_b32 s12, 0xffff0000
	s_nop 6
	v_cvt_pk_bf16_f32 v36, v138, v139
	v_cvt_pk_bf16_f32 v37, v140, v141
	v_add_co_u32_e32 v38, vcc, s12, v48
	v_cvt_pk_bf16_f32 v40, v146, v147
	s_nop 0
	v_addc_co_u32_e32 v39, vcc, -1, v49, vcc
	v_cvt_pk_bf16_f32 v41, v148, v149
	global_store_dwordx2 v[38:39], v[36:37], off
	global_store_dwordx2 v[48:49], v[40:41], off
	s_add_i32 s12, s16, 1
	s_cmp_lg_u32 s16, 3
	s_cselect_b32 s16, s12, 0
	s_add_i32 s11, s11, 1
	s_mov_b64 s[12:13], 0x20000
	v_lshl_add_u64 v[48:49], v[48:49], 0, s[12:13]
	s_waitcnt lgkmcnt(0)
	s_barrier
	s_cmpk_eq_i32 s11, 0x100
	s_cbranch_scc0 .Lch_comp_loop
	s_branch .LBB0_639
